# P2 idle-tail weight transposes: the 32 k-scale loads of an item batched after its weight loads (were 16 serialized round trips)
# speedup vs baseline: 1.0050x; 1.0050x over previous
; #define LAS __attribute__((address_space(3)))
; __device__ __forceinline__ void p0_transpose_item(const float* W, int ldw, int col0, int K, bf16* WT, int row_off, const float* kscale, LAS float* scr, int item, int nblk, int lane) {
;     const int kb = item / nblk, nb = item % nblk, k0 = 64 * kb, n0 = 32 * nb;
;     float tv[32];
; #pragma unroll
;     for (int i = 0; i < 32; ++i) { const int kk = 2 * i + (lane >> 5); tv[i] = W[(size_t)(k0 + kk) * ldw + col0 + n0 + (lane & 31)]; }
; #pragma unroll
;     for (int i = 0; i < 32; ++i) { const int kk = 2 * i + (lane >> 5); float v = tv[i]; if (kscale) v *= kscale[k0 + kk]; scr[kk * 33 + (lane & 31)] = v; }
; __device__ __forceinline__ void prep_weights_late(const Args& a, LAS unsigned char* lds, int wave, int lane, int widx, int nwork) {
;     ...
;         if (r < 512) { const int hf = r >> 8;
;             p0_transpose_item(a.in[15] + (size_t)hf * 512 * 1024, 1024, 0, 512, WoutT + (size_t)hf * 1024 * 512, 0, a.in[14] + hf * 512, scr, r & 255, 32, lane); continue; }
.LBB0_471:
	s_ashr_i32 s10, s56, 8
	s_ashr_i32 s11, s10, 31
	s_lshl_b64 s[2:3], s[10:11], 21
	s_add_u32 s2, s22, s2
	s_addc_u32 s3, s23, s3
	s_lshl_b32 s12, s10, 9
	s_ashr_i32 s13, s12, 31
	s_lshl_b64 s[12:13], s[12:13], 2
	s_add_u32 s12, s20, s12
	s_addc_u32 s13, s21, s13
	s_lshl_b32 s8, s56, 1
	s_and_b32 s57, s8, 0x1c0
	v_or_b32_e32 v48, s57, v1
	s_and_b32 s8, s28, 0x3e0
	v_lshlrev_b32_e32 v2, 10, v48
	v_or3_b32 v2, v2, v60, s8
	v_lshlrev_b32_e32 v2, 2, v2
	v_lshl_add_u64 v[20:21], s[2:3], 0, v[2:3]
	v_add_co_u32_e32 v4, vcc, s43, v20
	global_load_dword v46, v2, s[2:3]
	s_nop 0
	v_addc_co_u32_e32 v5, vcc, 0, v21, vcc
	global_load_dword v47, v[4:5], off
	s_movk_i32 s2, 0x4000
	v_add_co_u32_e32 v4, vcc, s2, v20
	s_mov_b32 s2, 0x8000
	s_nop 0
	v_addc_co_u32_e32 v5, vcc, 0, v21, vcc
	global_load_dword v18, v[4:5], off
	v_add_co_u32_e32 v4, vcc, s44, v20
	v_add_lshl_u32 v37, v1, s57, 2
	s_nop 0
	v_addc_co_u32_e32 v5, vcc, 0, v21, vcc
	global_load_dword v19, v[4:5], off
	v_add_co_u32_e32 v4, vcc, s2, v20
	s_mov_b32 s2, 0xc000
	s_nop 0
	v_addc_co_u32_e32 v5, vcc, 0, v21, vcc
	global_load_dword v44, v[4:5], off
	v_add_co_u32_e32 v4, vcc, s45, v20
	s_nop 1
	v_addc_co_u32_e32 v5, vcc, 0, v21, vcc
	global_load_dword v45, v[4:5], off
	v_add_co_u32_e32 v4, vcc, s2, v20
	s_mov_b32 s2, 0x10000
	s_nop 0
	v_addc_co_u32_e32 v5, vcc, 0, v21, vcc
	global_load_dword v16, v[4:5], off
	v_add_co_u32_e32 v4, vcc, s46, v20
	s_nop 1
	v_addc_co_u32_e32 v5, vcc, 0, v21, vcc
	global_load_dword v17, v[4:5], off
	v_add_co_u32_e32 v4, vcc, s2, v20
	s_nop 1
	v_addc_co_u32_e32 v5, vcc, 0, v21, vcc
	global_load_dword v42, v[4:5], off
	v_add_co_u32_e32 v4, vcc, s47, v20
	s_nop 1
	v_addc_co_u32_e32 v5, vcc, 0, v21, vcc
	global_load_dword v43, v[4:5], off
	v_add_co_u32_e32 v4, vcc, s33, v20
	s_nop 1
	v_addc_co_u32_e32 v5, vcc, 0, v21, vcc
	global_load_dword v14, v[4:5], off
	v_add_co_u32_e32 v4, vcc, s48, v20
	s_nop 1
	v_addc_co_u32_e32 v5, vcc, 0, v21, vcc
	global_load_dword v15, v[4:5], off
	v_add_co_u32_e32 v4, vcc, s34, v20
	s_nop 1
	v_addc_co_u32_e32 v5, vcc, 0, v21, vcc
	global_load_dword v40, v[4:5], off
	v_add_co_u32_e32 v4, vcc, s49, v20
	s_nop 1
	v_addc_co_u32_e32 v5, vcc, 0, v21, vcc
	global_load_dword v41, v[4:5], off
	v_add_co_u32_e32 v4, vcc, s35, v20
	s_nop 1
	v_addc_co_u32_e32 v5, vcc, 0, v21, vcc
	global_load_dword v12, v[4:5], off
	v_add_co_u32_e32 v4, vcc, s50, v20
	s_nop 1
	v_addc_co_u32_e32 v5, vcc, 0, v21, vcc
	global_load_dword v13, v[4:5], off
	v_add_co_u32_e32 v4, vcc, s36, v20
	s_nop 1
	v_addc_co_u32_e32 v5, vcc, 0, v21, vcc
	global_load_dword v38, v[4:5], off
	v_add_co_u32_e32 v4, vcc, s51, v20
	s_nop 1
	v_addc_co_u32_e32 v5, vcc, 0, v21, vcc
	global_load_dword v39, v[4:5], off
	v_add_co_u32_e32 v4, vcc, s37, v20
	s_nop 1
	v_addc_co_u32_e32 v5, vcc, 0, v21, vcc
	global_load_dword v10, v[4:5], off
	v_add_co_u32_e32 v4, vcc, s52, v20
	s_nop 1
	v_addc_co_u32_e32 v5, vcc, 0, v21, vcc
	global_load_dword v11, v[4:5], off
	v_add_co_u32_e32 v4, vcc, s38, v20
	s_nop 1
	v_addc_co_u32_e32 v5, vcc, 0, v21, vcc
	global_load_dword v35, v[4:5], off
	v_add_co_u32_e32 v4, vcc, s53, v20
	s_nop 1
	v_addc_co_u32_e32 v5, vcc, 0, v21, vcc
	global_load_dword v36, v[4:5], off
	v_add_co_u32_e32 v4, vcc, s39, v20
	s_nop 1
	v_addc_co_u32_e32 v5, vcc, 0, v21, vcc
	global_load_dword v8, v[4:5], off
	v_add_co_u32_e32 v4, vcc, s54, v20
	s_nop 1
	v_addc_co_u32_e32 v5, vcc, 0, v21, vcc
	global_load_dword v9, v[4:5], off
	v_add_co_u32_e32 v4, vcc, s40, v20
	s_nop 1
	v_addc_co_u32_e32 v5, vcc, 0, v21, vcc
	global_load_dword v33, v[4:5], off
	v_add_co_u32_e32 v4, vcc, s55, v20
	s_nop 1
	v_addc_co_u32_e32 v5, vcc, 0, v21, vcc
	global_load_dword v34, v[4:5], off
	v_add_co_u32_e32 v4, vcc, s41, v20
	s_nop 1
	v_addc_co_u32_e32 v5, vcc, 0, v21, vcc
	global_load_dword v6, v[4:5], off
	v_add_co_u32_e32 v4, vcc, 0x36000, v20
	s_nop 1
	v_addc_co_u32_e32 v5, vcc, 0, v21, vcc
	global_load_dword v7, v[4:5], off
	v_add_co_u32_e32 v4, vcc, s42, v20
	s_nop 1
	v_addc_co_u32_e32 v5, vcc, 0, v21, vcc
	global_load_dword v2, v[4:5], off
	v_add_co_u32_e32 v4, vcc, 0x3a000, v20
	s_nop 1
	v_addc_co_u32_e32 v5, vcc, 0, v21, vcc
	global_load_dword v32, v[4:5], off
	v_add_co_u32_e32 v4, vcc, 0x3c000, v20
	s_nop 1
	v_addc_co_u32_e32 v5, vcc, 0, v21, vcc
	v_add_co_u32_e32 v20, vcc, 0x3e000, v20
	global_load_dword v4, v[4:5], off
	s_nop 0
	v_addc_co_u32_e32 v21, vcc, 0, v21, vcc
	global_load_dword v5, v[20:21], off
	s_andn2_b64 vcc, exec, s[4:5]
	s_cbranch_vccnz .Lks_skip_0
	s_waitcnt vmcnt(20)
	v_lshlrev_b32_e32 v186, 2, v48
	global_load_dword v186, v186, s[12:13]
	global_load_dword v187, v37, s[12:13] offset:8
	global_load_dword v188, v37, s[12:13] offset:16
	global_load_dword v189, v37, s[12:13] offset:24
	global_load_dword v190, v37, s[12:13] offset:32
	global_load_dword v191, v37, s[12:13] offset:40
	global_load_dword v192, v37, s[12:13] offset:48
	global_load_dword v193, v37, s[12:13] offset:56
	global_load_dword v194, v37, s[12:13] offset:64
	global_load_dword v195, v37, s[12:13] offset:72
	global_load_dword v196, v37, s[12:13] offset:80
	global_load_dword v197, v37, s[12:13] offset:88
	global_load_dword v198, v37, s[12:13] offset:96
	global_load_dword v199, v37, s[12:13] offset:104
	global_load_dword v200, v37, s[12:13] offset:112
	global_load_dword v201, v37, s[12:13] offset:120
	global_load_dword v202, v37, s[12:13] offset:128
	global_load_dword v203, v37, s[12:13] offset:136
	global_load_dword v204, v37, s[12:13] offset:144
	global_load_dword v205, v37, s[12:13] offset:152
	global_load_dword v206, v37, s[12:13] offset:160
	global_load_dword v207, v37, s[12:13] offset:168
	global_load_dword v208, v37, s[12:13] offset:176
	global_load_dword v209, v37, s[12:13] offset:184
	global_load_dword v210, v37, s[12:13] offset:192
	global_load_dword v211, v37, s[12:13] offset:200
	global_load_dword v212, v37, s[12:13] offset:208
	global_load_dword v213, v37, s[12:13] offset:216
	global_load_dword v214, v37, s[12:13] offset:224
	global_load_dword v215, v37, s[12:13] offset:232
	global_load_dword v216, v37, s[12:13] offset:240
	global_load_dword v217, v37, s[12:13] offset:248
.Lks_skip_0:
	v_cndmask_b32_e64 v20, 0, 1, s[4:5]
	v_cmp_ne_u32_e64 s[2:3], 1, v20
	s_andn2_b64 vcc, exec, s[4:5]
	s_cbranch_vccnz .LBB0_494
	s_waitcnt vmcnt(0)
	v_mov_b32_e32 v20, v186
	s_nop 0
	v_mov_b32_e32 v21, v187
	s_waitcnt vmcnt(1)
	v_mul_f32_e32 v20, v46, v20
	ds_write_b32 v22, v20
	s_waitcnt vmcnt(0)
	v_mul_f32_e32 v21, v47, v21
	v_add_u32_e32 v20, v61, v67
	ds_write_b32 v20, v21
	v_mov_b32_e32 v20, v188
	v_mov_b32_e32 v21, v189
	s_waitcnt vmcnt(0)
	v_pk_mul_f32 v[20:21], v[18:19], v[20:21]
	s_cbranch_execnz .LBB0_474

; __device__ __forceinline__ void p0_transpose_item(const float* W, int ldw, int col0, int K, bf16* WT, int row_off, const float* kscale, LAS float* scr, int item, int nblk, int lane) {
;     ...
;     for (int i = 0; i < 32; ++i) { const int kk = 2 * i + (lane >> 5); float v = tv[i]; if (kscale) v *= kscale[k0 + kk]; scr[kk * 33 + (lane & 31)] = v; }
.LBB0_474:
	s_waitcnt vmcnt(29)
	v_add_u32_e32 v18, v61, v68
	s_and_b64 vcc, exec, s[2:3]
	ds_write2_b32 v18, v20, v21 offset1:66
	s_cbranch_vccnz .LBB0_495
	v_mov_b32_e32 v18, v190
	v_mov_b32_e32 v19, v191
	v_add_u32_e32 v20, v61, v69
	s_waitcnt vmcnt(1)
	v_mul_f32_e32 v18, v44, v18
	s_waitcnt vmcnt(0)
	v_mul_f32_e32 v19, v45, v19
	ds_write2_b32 v20, v18, v19 offset1:66
	v_mov_b32_e32 v18, v192
	v_mov_b32_e32 v19, v193
	s_waitcnt vmcnt(0)
	v_pk_mul_f32 v[18:19], v[16:17], v[18:19]
	s_cbranch_execnz .LBB0_477

; __device__ __forceinline__ void p0_transpose_item(const float* W, int ldw, int col0, int K, bf16* WT, int row_off, const float* kscale, LAS float* scr, int item, int nblk, int lane) {
;     ...
;     for (int i = 0; i < 32; ++i) { const int kk = 2 * i + (lane >> 5); float v = tv[i]; if (kscale) v *= kscale[k0 + kk]; scr[kk * 33 + (lane & 31)] = v; }
.LBB0_477:
	s_waitcnt vmcnt(25)
	v_add_u32_e32 v16, v61, v70
	s_and_b64 vcc, exec, s[2:3]
	ds_write2_b32 v16, v18, v19 offset1:66
	s_cbranch_vccnz .LBB0_496
	v_mov_b32_e32 v16, v194
	v_mov_b32_e32 v17, v195
	v_add_u32_e32 v18, v61, v71
	s_waitcnt vmcnt(1)
	v_mul_f32_e32 v16, v42, v16
	s_waitcnt vmcnt(0)
	v_mul_f32_e32 v17, v43, v17
	ds_write2_b32 v18, v16, v17 offset1:66
	v_mov_b32_e32 v16, v196
	v_mov_b32_e32 v17, v197
	s_waitcnt vmcnt(0)
	v_pk_mul_f32 v[16:17], v[14:15], v[16:17]
	s_cbranch_execnz .LBB0_480

; __device__ __forceinline__ void p0_transpose_item(const float* W, int ldw, int col0, int K, bf16* WT, int row_off, const float* kscale, LAS float* scr, int item, int nblk, int lane) {
;     ...
;     for (int i = 0; i < 32; ++i) { const int kk = 2 * i + (lane >> 5); float v = tv[i]; if (kscale) v *= kscale[k0 + kk]; scr[kk * 33 + (lane & 31)] = v; }
.LBB0_480:
	s_waitcnt vmcnt(21)
	v_add_u32_e32 v14, v61, v72
	s_and_b64 vcc, exec, s[2:3]
	ds_write2_b32 v14, v16, v17 offset1:66
	s_cbranch_vccnz .LBB0_497
	v_mov_b32_e32 v14, v198
	v_mov_b32_e32 v15, v199
	v_add_u32_e32 v16, v61, v73
	s_waitcnt vmcnt(1)
	v_mul_f32_e32 v14, v40, v14
	s_waitcnt vmcnt(0)
	v_mul_f32_e32 v15, v41, v15
	ds_write2_b32 v16, v14, v15 offset1:66
	v_mov_b32_e32 v14, v200
	v_mov_b32_e32 v15, v201
	s_waitcnt vmcnt(0)
	v_pk_mul_f32 v[14:15], v[12:13], v[14:15]
	s_cbranch_execnz .LBB0_483

; __device__ __forceinline__ void p0_transpose_item(const float* W, int ldw, int col0, int K, bf16* WT, int row_off, const float* kscale, LAS float* scr, int item, int nblk, int lane) {
;     ...
;     for (int i = 0; i < 32; ++i) { const int kk = 2 * i + (lane >> 5); float v = tv[i]; if (kscale) v *= kscale[k0 + kk]; scr[kk * 33 + (lane & 31)] = v; }
.LBB0_483:
	s_waitcnt vmcnt(17)
	v_add_u32_e32 v12, v61, v74
	s_and_b64 vcc, exec, s[2:3]
	ds_write2_b32 v12, v14, v15 offset1:66
	s_cbranch_vccnz .LBB0_498
	v_mov_b32_e32 v12, v202
	v_mov_b32_e32 v13, v203
	v_add_u32_e32 v14, v61, v75
	s_waitcnt vmcnt(1)
	v_mul_f32_e32 v12, v38, v12
	s_waitcnt vmcnt(0)
	v_mul_f32_e32 v13, v39, v13
	ds_write2_b32 v14, v12, v13 offset1:66
	v_mov_b32_e32 v12, v204
	v_mov_b32_e32 v13, v205
	s_waitcnt vmcnt(0)
	v_pk_mul_f32 v[12:13], v[10:11], v[12:13]
	s_cbranch_execnz .LBB0_486

; __device__ __forceinline__ void p0_transpose_item(const float* W, int ldw, int col0, int K, bf16* WT, int row_off, const float* kscale, LAS float* scr, int item, int nblk, int lane) {
;     ...
;     for (int i = 0; i < 32; ++i) { const int kk = 2 * i + (lane >> 5); float v = tv[i]; if (kscale) v *= kscale[k0 + kk]; scr[kk * 33 + (lane & 31)] = v; }
.LBB0_486:
	s_waitcnt vmcnt(13)
	v_add_u32_e32 v10, v61, v76
	s_and_b64 vcc, exec, s[2:3]
	ds_write2_b32 v10, v12, v13 offset1:66
	s_cbranch_vccnz .LBB0_499
	v_mov_b32_e32 v10, v206
	v_mov_b32_e32 v11, v207
	v_add_u32_e32 v12, v61, v77
	s_waitcnt vmcnt(1)
	v_mul_f32_e32 v10, v35, v10
	s_waitcnt vmcnt(0)
	v_mul_f32_e32 v11, v36, v11
	ds_write2_b32 v12, v10, v11 offset1:66
	v_mov_b32_e32 v10, v208
	v_mov_b32_e32 v11, v209
	s_waitcnt vmcnt(0)
	v_pk_mul_f32 v[10:11], v[8:9], v[10:11]
	s_cbranch_execnz .LBB0_489

; __device__ __forceinline__ void p0_transpose_item(const float* W, int ldw, int col0, int K, bf16* WT, int row_off, const float* kscale, LAS float* scr, int item, int nblk, int lane) {
;     ...
;     for (int i = 0; i < 32; ++i) { const int kk = 2 * i + (lane >> 5); float v = tv[i]; if (kscale) v *= kscale[k0 + kk]; scr[kk * 33 + (lane & 31)] = v; }
.LBB0_489:
	v_add_u32_e32 v12, v61, v77
	s_waitcnt vmcnt(12)
	ds_write2_b32 v12, v10, v11 offset0:132 offset1:198
	s_and_b64 vcc, exec, s[2:3]
	v_add_u32_e32 v10, 0x400, v12
	s_cbranch_vccnz .LBB0_500
	v_mov_b32_e32 v8, v210
	v_mov_b32_e32 v9, v211
	s_waitcnt vmcnt(1)
	v_mul_f32_e32 v8, v33, v8
	s_waitcnt vmcnt(0)
	v_mul_f32_e32 v9, v34, v9
	ds_write2_b32 v10, v8, v9 offset0:8 offset1:74
	v_mov_b32_e32 v8, v212
	v_mov_b32_e32 v9, v213
	s_waitcnt vmcnt(0)
	v_pk_mul_f32 v[8:9], v[6:7], v[8:9]
	s_cbranch_execnz .LBB0_492

; __device__ __forceinline__ void p0_transpose_item(const float* W, int ldw, int col0, int K, bf16* WT, int row_off, const float* kscale, LAS float* scr, int item, int nblk, int lane) {
;     ...
;     for (int i = 0; i < 32; ++i) { const int kk = 2 * i + (lane >> 5); float v = tv[i]; if (kscale) v *= kscale[k0 + kk]; scr[kk * 33 + (lane & 31)] = v; }
.LBB0_492:
	s_waitcnt vmcnt(8)
	ds_write2_b32 v10, v8, v9 offset0:140 offset1:206
	s_and_b64 vcc, exec, s[2:3]
	v_add_u32_e32 v8, 0x800, v12
	s_cbranch_vccnz .LBB0_501
	v_mov_b32_e32 v6, v214
	v_mov_b32_e32 v7, v215
	s_waitcnt vmcnt(1)
	v_mul_f32_e32 v6, v2, v6
	s_waitcnt vmcnt(0)
	v_mul_f32_e32 v7, v32, v7
	ds_write2_b32 v8, v6, v7 offset0:16 offset1:82
	v_mov_b32_e32 v6, v216
	v_mov_b32_e32 v7, v217
	s_waitcnt vmcnt(0)
	v_pk_mul_f32 v[6:7], v[4:5], v[6:7]
	s_cbranch_execnz .LBB0_462
	s_branch .LBB0_461

; #define LAS __attribute__((address_space(3)))
; __device__ __forceinline__ void p0_transpose_item(const float* W, int ldw, int col0, int K, bf16* WT, int row_off, const float* kscale, LAS float* scr, int item, int nblk, int lane) {
;     const int kb = item / nblk, nb = item % nblk, k0 = 64 * kb, n0 = 32 * nb;
;     float tv[32];
; #pragma unroll
;     for (int i = 0; i < 32; ++i) { const int kk = 2 * i + (lane >> 5); tv[i] = W[(size_t)(k0 + kk) * ldw + col0 + n0 + (lane & 31)]; }
; #pragma unroll
;     for (int i = 0; i < 32; ++i) { const int kk = 2 * i + (lane >> 5); float v = tv[i]; if (kscale) v *= kscale[k0 + kk]; scr[kk * 33 + (lane & 31)] = v; }
.LBB0_526:
	s_ashr_i32 s10, s56, 8
	s_ashr_i32 s11, s10, 31
	s_lshl_b64 s[2:3], s[10:11], 21
	s_add_u32 s2, s22, s2
	s_addc_u32 s3, s23, s3
	s_lshl_b32 s12, s10, 9
	s_ashr_i32 s13, s12, 31
	s_lshl_b64 s[12:13], s[12:13], 2
	s_add_u32 s12, s20, s12
	s_addc_u32 s13, s21, s13
	s_lshl_b32 s8, s56, 1
	s_and_b32 s57, s8, 0x1c0
	v_or_b32_e32 v48, s57, v1
	s_and_b32 s8, s28, 0x3e0
	v_lshlrev_b32_e32 v2, 10, v48
	v_or3_b32 v2, v2, v60, s8
	v_lshlrev_b32_e32 v2, 2, v2
	v_lshl_add_u64 v[20:21], s[2:3], 0, v[2:3]
	v_add_co_u32_e32 v4, vcc, s43, v20
	global_load_dword v46, v2, s[2:3]
	s_nop 0
	v_addc_co_u32_e32 v5, vcc, 0, v21, vcc
	global_load_dword v47, v[4:5], off
	s_movk_i32 s2, 0x4000
	v_add_co_u32_e32 v4, vcc, s2, v20
	s_mov_b32 s2, 0x8000
	s_nop 0
	v_addc_co_u32_e32 v5, vcc, 0, v21, vcc
	global_load_dword v18, v[4:5], off
	v_add_co_u32_e32 v4, vcc, s44, v20
	v_add_u32_e32 v49, v61, v67
	s_nop 0
	v_addc_co_u32_e32 v5, vcc, 0, v21, vcc
	global_load_dword v19, v[4:5], off
	v_add_co_u32_e32 v4, vcc, s2, v20
	s_mov_b32 s2, 0xc000
	s_nop 0
	v_addc_co_u32_e32 v5, vcc, 0, v21, vcc
	global_load_dword v44, v[4:5], off
	v_add_co_u32_e32 v4, vcc, s45, v20
	v_add_lshl_u32 v40, v1, s57, 2
	s_nop 0
	v_addc_co_u32_e32 v5, vcc, 0, v21, vcc
	global_load_dword v45, v[4:5], off
	v_add_co_u32_e32 v4, vcc, s2, v20
	s_nop 1
	v_addc_co_u32_e32 v5, vcc, 0, v21, vcc
	global_load_dword v16, v[4:5], off
	v_add_co_u32_e32 v4, vcc, s46, v20
	s_nop 1
	v_addc_co_u32_e32 v5, vcc, 0, v21, vcc
	global_load_dword v17, v[4:5], off
	v_add_co_u32_e32 v4, vcc, s31, v20
	s_nop 1
	v_addc_co_u32_e32 v5, vcc, 0, v21, vcc
	global_load_dword v42, v[4:5], off
	v_add_co_u32_e32 v4, vcc, s47, v20
	s_nop 1
	v_addc_co_u32_e32 v5, vcc, 0, v21, vcc
	global_load_dword v43, v[4:5], off
	v_add_co_u32_e32 v4, vcc, s33, v20
	s_nop 1
	v_addc_co_u32_e32 v5, vcc, 0, v21, vcc
	global_load_dword v14, v[4:5], off
	v_add_co_u32_e32 v4, vcc, s48, v20
	s_nop 1
	v_addc_co_u32_e32 v5, vcc, 0, v21, vcc
	global_load_dword v15, v[4:5], off
	v_add_co_u32_e32 v4, vcc, s34, v20
	s_nop 1
	v_addc_co_u32_e32 v5, vcc, 0, v21, vcc
	global_load_dword v39, v[4:5], off
	v_add_co_u32_e32 v4, vcc, s49, v20
	s_nop 1
	v_addc_co_u32_e32 v5, vcc, 0, v21, vcc
	global_load_dword v41, v[4:5], off
	v_add_co_u32_e32 v4, vcc, s35, v20
	s_nop 1
	v_addc_co_u32_e32 v5, vcc, 0, v21, vcc
	global_load_dword v12, v[4:5], off
	v_add_co_u32_e32 v4, vcc, s50, v20
	s_nop 1
	v_addc_co_u32_e32 v5, vcc, 0, v21, vcc
	global_load_dword v13, v[4:5], off
	v_add_co_u32_e32 v4, vcc, s36, v20
	s_nop 1
	v_addc_co_u32_e32 v5, vcc, 0, v21, vcc
	global_load_dword v37, v[4:5], off
	v_add_co_u32_e32 v4, vcc, s51, v20
	s_nop 1
	v_addc_co_u32_e32 v5, vcc, 0, v21, vcc
	global_load_dword v38, v[4:5], off
	v_add_co_u32_e32 v4, vcc, s37, v20
	s_nop 1
	v_addc_co_u32_e32 v5, vcc, 0, v21, vcc
	global_load_dword v10, v[4:5], off
	v_add_co_u32_e32 v4, vcc, s52, v20
	s_nop 1
	v_addc_co_u32_e32 v5, vcc, 0, v21, vcc
	global_load_dword v11, v[4:5], off
	v_add_co_u32_e32 v4, vcc, s38, v20
	s_nop 1
	v_addc_co_u32_e32 v5, vcc, 0, v21, vcc
	global_load_dword v35, v[4:5], off
	v_add_co_u32_e32 v4, vcc, s53, v20
	s_nop 1
	v_addc_co_u32_e32 v5, vcc, 0, v21, vcc
	global_load_dword v36, v[4:5], off
	v_add_co_u32_e32 v4, vcc, s39, v20
	s_nop 1
	v_addc_co_u32_e32 v5, vcc, 0, v21, vcc
	global_load_dword v8, v[4:5], off
	v_add_co_u32_e32 v4, vcc, s54, v20
	s_nop 1
	v_addc_co_u32_e32 v5, vcc, 0, v21, vcc
	global_load_dword v9, v[4:5], off
	v_add_co_u32_e32 v4, vcc, s40, v20
	s_nop 1
	v_addc_co_u32_e32 v5, vcc, 0, v21, vcc
	global_load_dword v33, v[4:5], off
	v_add_co_u32_e32 v4, vcc, s55, v20
	s_nop 1
	v_addc_co_u32_e32 v5, vcc, 0, v21, vcc
	global_load_dword v34, v[4:5], off
	v_add_co_u32_e32 v4, vcc, s41, v20
	s_nop 1
	v_addc_co_u32_e32 v5, vcc, 0, v21, vcc
	global_load_dword v6, v[4:5], off
	v_add_co_u32_e32 v4, vcc, 0x36000, v20
	s_nop 1
	v_addc_co_u32_e32 v5, vcc, 0, v21, vcc
	global_load_dword v7, v[4:5], off
	v_add_co_u32_e32 v4, vcc, s42, v20
	s_nop 1
	v_addc_co_u32_e32 v5, vcc, 0, v21, vcc
	global_load_dword v2, v[4:5], off
	v_add_co_u32_e32 v4, vcc, 0x3a000, v20
	s_nop 1
	v_addc_co_u32_e32 v5, vcc, 0, v21, vcc
	global_load_dword v32, v[4:5], off
	v_add_co_u32_e32 v4, vcc, 0x3c000, v20
	s_nop 1
	v_addc_co_u32_e32 v5, vcc, 0, v21, vcc
	v_add_co_u32_e32 v20, vcc, 0x3e000, v20
	global_load_dword v4, v[4:5], off
	s_nop 0
	v_addc_co_u32_e32 v21, vcc, 0, v21, vcc
	global_load_dword v5, v[20:21], off
	s_andn2_b64 vcc, exec, s[4:5]
	s_cbranch_vccnz .Lks_skip_1
	s_waitcnt vmcnt(20)
	v_lshlrev_b32_e32 v186, 2, v48
	global_load_dword v186, v186, s[12:13]
	global_load_dword v187, v40, s[12:13] offset:8
	global_load_dword v188, v40, s[12:13] offset:16
	global_load_dword v189, v40, s[12:13] offset:24
	global_load_dword v190, v40, s[12:13] offset:32
	global_load_dword v191, v40, s[12:13] offset:40
	global_load_dword v192, v40, s[12:13] offset:48
	global_load_dword v193, v40, s[12:13] offset:56
	global_load_dword v194, v40, s[12:13] offset:64
	global_load_dword v195, v40, s[12:13] offset:72
	global_load_dword v196, v40, s[12:13] offset:80
	global_load_dword v197, v40, s[12:13] offset:88
	global_load_dword v198, v40, s[12:13] offset:96
	global_load_dword v199, v40, s[12:13] offset:104
	global_load_dword v200, v40, s[12:13] offset:112
	global_load_dword v201, v40, s[12:13] offset:120
	global_load_dword v202, v40, s[12:13] offset:128
	global_load_dword v203, v40, s[12:13] offset:136
	global_load_dword v204, v40, s[12:13] offset:144
	global_load_dword v205, v40, s[12:13] offset:152
	global_load_dword v206, v40, s[12:13] offset:160
	global_load_dword v207, v40, s[12:13] offset:168
	global_load_dword v208, v40, s[12:13] offset:176
	global_load_dword v209, v40, s[12:13] offset:184
	global_load_dword v210, v40, s[12:13] offset:192
	global_load_dword v211, v40, s[12:13] offset:200
	global_load_dword v212, v40, s[12:13] offset:208
	global_load_dword v213, v40, s[12:13] offset:216
	global_load_dword v214, v40, s[12:13] offset:224
	global_load_dword v215, v40, s[12:13] offset:232
	global_load_dword v216, v40, s[12:13] offset:240
	global_load_dword v217, v40, s[12:13] offset:248
.Lks_skip_1:
	v_cndmask_b32_e64 v20, 0, 1, s[4:5]
	v_cmp_ne_u32_e64 s[2:3], 1, v20
	s_andn2_b64 vcc, exec, s[4:5]
	s_cbranch_vccnz .LBB0_549
	s_waitcnt vmcnt(0)
	v_mov_b32_e32 v20, v186
	s_nop 0
	v_mov_b32_e32 v21, v187
	s_waitcnt vmcnt(1)
	v_mul_f32_e32 v20, v46, v20
	s_waitcnt vmcnt(0)
	v_mul_f32_e32 v21, v47, v21
	ds_write_b32 v22, v20
	ds_write_b32 v49, v21
	v_mov_b32_e32 v20, v188
	v_mov_b32_e32 v21, v189
	s_waitcnt vmcnt(0)
	v_pk_mul_f32 v[20:21], v[18:19], v[20:21]
	s_cbranch_execnz .LBB0_529

; __device__ __forceinline__ void p0_transpose_item(const float* W, int ldw, int col0, int K, bf16* WT, int row_off, const float* kscale, LAS float* scr, int item, int nblk, int lane) {
;     ...
;     for (int i = 0; i < 32; ++i) { const int kk = 2 * i + (lane >> 5); float v = tv[i]; if (kscale) v *= kscale[k0 + kk]; scr[kk * 33 + (lane & 31)] = v; }
.LBB0_529:
	s_waitcnt vmcnt(29)
	v_add_u32_e32 v18, v61, v68
	ds_write2_b32 v18, v20, v21 offset1:66
	s_and_b64 vcc, exec, s[2:3]
	v_add_u32_e32 v20, v61, v69
	s_cbranch_vccnz .LBB0_550
	v_mov_b32_e32 v18, v190
	v_mov_b32_e32 v19, v191
	s_waitcnt vmcnt(1)
	v_mul_f32_e32 v18, v44, v18
	s_waitcnt vmcnt(0)
	v_mul_f32_e32 v19, v45, v19
	ds_write2_b32 v20, v18, v19 offset1:66
	v_mov_b32_e32 v18, v192
	v_mov_b32_e32 v19, v193
	s_waitcnt vmcnt(0)
	v_pk_mul_f32 v[18:19], v[16:17], v[18:19]
	s_cbranch_execnz .LBB0_532

; __device__ __forceinline__ void p0_transpose_item(const float* W, int ldw, int col0, int K, bf16* WT, int row_off, const float* kscale, LAS float* scr, int item, int nblk, int lane) {
;     ...
;     for (int i = 0; i < 32; ++i) { const int kk = 2 * i + (lane >> 5); float v = tv[i]; if (kscale) v *= kscale[k0 + kk]; scr[kk * 33 + (lane & 31)] = v; }
.LBB0_532:
	s_waitcnt vmcnt(25)
	v_add_u32_e32 v16, v61, v70
	ds_write2_b32 v16, v18, v19 offset1:66
	s_and_b64 vcc, exec, s[2:3]
	v_add_u32_e32 v18, v61, v71
	s_cbranch_vccnz .LBB0_551
	v_mov_b32_e32 v16, v194
	v_mov_b32_e32 v17, v195
	s_waitcnt vmcnt(1)
	v_mul_f32_e32 v16, v42, v16
	s_waitcnt vmcnt(0)
	v_mul_f32_e32 v17, v43, v17
	ds_write2_b32 v18, v16, v17 offset1:66
	v_mov_b32_e32 v16, v196
	v_mov_b32_e32 v17, v197
	s_waitcnt vmcnt(0)
	v_pk_mul_f32 v[16:17], v[14:15], v[16:17]
	s_cbranch_execnz .LBB0_535

; __device__ __forceinline__ void p0_transpose_item(const float* W, int ldw, int col0, int K, bf16* WT, int row_off, const float* kscale, LAS float* scr, int item, int nblk, int lane) {
;     ...
;     for (int i = 0; i < 32; ++i) { const int kk = 2 * i + (lane >> 5); float v = tv[i]; if (kscale) v *= kscale[k0 + kk]; scr[kk * 33 + (lane & 31)] = v; }
.LBB0_535:
	s_waitcnt vmcnt(21)
	v_add_u32_e32 v14, v61, v72
	ds_write2_b32 v14, v16, v17 offset1:66
	s_and_b64 vcc, exec, s[2:3]
	v_add_u32_e32 v16, v61, v73
	s_cbranch_vccnz .LBB0_552
	v_mov_b32_e32 v14, v198
	v_mov_b32_e32 v15, v199
	s_waitcnt vmcnt(1)
	v_mul_f32_e32 v14, v39, v14
	s_waitcnt vmcnt(0)
	v_mul_f32_e32 v15, v41, v15
	ds_write2_b32 v16, v14, v15 offset1:66
	v_mov_b32_e32 v14, v200
	v_mov_b32_e32 v15, v201
	s_waitcnt vmcnt(0)
	v_pk_mul_f32 v[14:15], v[12:13], v[14:15]
	s_cbranch_execnz .LBB0_538

; __device__ __forceinline__ void p0_transpose_item(const float* W, int ldw, int col0, int K, bf16* WT, int row_off, const float* kscale, LAS float* scr, int item, int nblk, int lane) {
;     ...
;     for (int i = 0; i < 32; ++i) { const int kk = 2 * i + (lane >> 5); float v = tv[i]; if (kscale) v *= kscale[k0 + kk]; scr[kk * 33 + (lane & 31)] = v; }
.LBB0_538:
	s_waitcnt vmcnt(17)
	v_add_u32_e32 v12, v61, v74
	ds_write2_b32 v12, v14, v15 offset1:66
	s_and_b64 vcc, exec, s[2:3]
	v_add_u32_e32 v14, v61, v75
	s_cbranch_vccnz .LBB0_553
	v_mov_b32_e32 v12, v202
	v_mov_b32_e32 v13, v203
	s_waitcnt vmcnt(1)
	v_mul_f32_e32 v12, v37, v12
	s_waitcnt vmcnt(0)
	v_mul_f32_e32 v13, v38, v13
	ds_write2_b32 v14, v12, v13 offset1:66
	v_mov_b32_e32 v12, v204
	v_mov_b32_e32 v13, v205
	s_waitcnt vmcnt(0)
	v_pk_mul_f32 v[12:13], v[10:11], v[12:13]
	s_cbranch_execnz .LBB0_541

; __device__ __forceinline__ void p0_transpose_item(const float* W, int ldw, int col0, int K, bf16* WT, int row_off, const float* kscale, LAS float* scr, int item, int nblk, int lane) {
;     ...
;     for (int i = 0; i < 32; ++i) { const int kk = 2 * i + (lane >> 5); float v = tv[i]; if (kscale) v *= kscale[k0 + kk]; scr[kk * 33 + (lane & 31)] = v; }
.LBB0_541:
	s_waitcnt vmcnt(13)
	v_add_u32_e32 v10, v61, v76
	ds_write2_b32 v10, v12, v13 offset1:66
	s_and_b64 vcc, exec, s[2:3]
	v_add_u32_e32 v12, v61, v77
	s_cbranch_vccnz .LBB0_554
	v_mov_b32_e32 v10, v206
	v_mov_b32_e32 v11, v207
	s_waitcnt vmcnt(1)
	v_mul_f32_e32 v10, v35, v10
	s_waitcnt vmcnt(0)
	v_mul_f32_e32 v11, v36, v11
	ds_write2_b32 v12, v10, v11 offset1:66
	v_mov_b32_e32 v10, v208
	v_mov_b32_e32 v11, v209
	s_waitcnt vmcnt(0)
	v_pk_mul_f32 v[10:11], v[8:9], v[10:11]
	s_cbranch_execnz .LBB0_544

; __device__ __forceinline__ void p0_transpose_item(const float* W, int ldw, int col0, int K, bf16* WT, int row_off, const float* kscale, LAS float* scr, int item, int nblk, int lane) {
;     ...
;     for (int i = 0; i < 32; ++i) { const int kk = 2 * i + (lane >> 5); float v = tv[i]; if (kscale) v *= kscale[k0 + kk]; scr[kk * 33 + (lane & 31)] = v; }
.LBB0_544:
	s_waitcnt vmcnt(12)
	ds_write2_b32 v12, v10, v11 offset0:132 offset1:198
	s_and_b64 vcc, exec, s[2:3]
	v_add_u32_e32 v10, 0x400, v12
	s_cbranch_vccnz .LBB0_555
	v_mov_b32_e32 v8, v210
	v_mov_b32_e32 v9, v211
	s_waitcnt vmcnt(1)
	v_mul_f32_e32 v8, v33, v8
	s_waitcnt vmcnt(0)
	v_mul_f32_e32 v9, v34, v9
	ds_write2_b32 v10, v8, v9 offset0:8 offset1:74
	v_mov_b32_e32 v8, v212
	v_mov_b32_e32 v9, v213
	s_waitcnt vmcnt(0)
	v_pk_mul_f32 v[8:9], v[6:7], v[8:9]
	s_cbranch_execnz .LBB0_547

; __device__ __forceinline__ void p0_transpose_item(const float* W, int ldw, int col0, int K, bf16* WT, int row_off, const float* kscale, LAS float* scr, int item, int nblk, int lane) {
;     ...
;     for (int i = 0; i < 32; ++i) { const int kk = 2 * i + (lane >> 5); float v = tv[i]; if (kscale) v *= kscale[k0 + kk]; scr[kk * 33 + (lane & 31)] = v; }
.LBB0_547:
	s_waitcnt vmcnt(8)
	ds_write2_b32 v10, v8, v9 offset0:140 offset1:206
	s_and_b64 vcc, exec, s[2:3]
	v_add_u32_e32 v8, 0x800, v12
	s_cbranch_vccnz .LBB0_556
	v_mov_b32_e32 v9, v214
	v_mov_b32_e32 v10, v215
	v_mov_b32_e32 v6, v216
	v_mov_b32_e32 v7, v217
	s_waitcnt vmcnt(3)
	v_mul_f32_e32 v9, v2, v9
	s_waitcnt vmcnt(2)
	v_mul_f32_e32 v10, v32, v10
	ds_write2_b32 v8, v9, v10 offset0:16 offset1:82
	s_waitcnt vmcnt(0)
	v_pk_mul_f32 v[6:7], v[4:5], v[6:7]
	s_cbranch_execnz .LBB0_517
	s_branch .LBB0_516
